# code placement: GEMM K-loop heads at byte phase 32 mod 64
# baseline (speedup 1.0000x reference)
.LBB0_223:
	v_add_u32_e32 v155, s81, v17
	v_add_u32_e32 v156, 0x2000, v155
	v_readfirstlane_b32 s17, v155
	v_lshl_add_u64 v[4:5], v[4:5], 0, s[6:7]
	s_mov_b32 m0, s17
	v_readfirstlane_b32 s17, v156
	v_add_u32_e32 v157, 0x8000, v148
	s_waitcnt vmcnt(4)
	s_barrier
	global_load_lds_dwordx4 v[4:5], off
	v_lshl_add_u64 v[4:5], v[6:7], 0, s[6:7]
	s_mov_b32 m0, s17
	v_readfirstlane_b32 s17, v157
	v_add_u32_e32 v158, 0xa000, v148
	global_load_lds_dwordx4 v[4:5], off
	v_lshl_add_u64 v[4:5], v[8:9], 0, s[6:7]
	s_mov_b32 m0, s17
	v_readfirstlane_b32 s17, v158
	v_add_u32_e32 v159, s82, v17
	global_load_lds_dwordx4 v[4:5], off
	v_lshl_add_u64 v[4:5], v[10:11], 0, s[6:7]
	s_mov_b32 m0, s17
	v_readfirstlane_b32 s17, v159
	v_add_u32_e32 v160, 0x2000, v159
	global_load_lds_dwordx4 v[4:5], off
	v_lshl_add_u64 v[4:5], v[12:13], 0, s[6:7]
	s_mov_b32 m0, s17
	v_readfirstlane_b32 s17, v160
	global_load_lds_dwordx4 v[4:5], off
	v_lshl_add_u64 v[4:5], v[14:15], 0, s[6:7]
	s_mov_b32 m0, s17
	v_and_b32_e32 v18, 15, v16
	global_load_lds_dwordx4 v[4:5], off
	v_lshlrev_b32_e32 v5, 2, v16
	v_and_b32_e32 v19, 48, v16
	v_lshlrev_b32_e32 v4, 6, v18
	v_and_b32_e32 v5, 32, v5
	v_bitop3_b32 v4, v4, v5, v19 bitop3:0x36
	v_add_u32_e32 v6, s33, v4
	v_add_u32_e32 v7, s80, v4
	v_add_u32_e32 v8, s81, v4
	v_add_u32_e32 v9, s82, v4
	s_lshl_b32 s60, s1, 13
	v_add_u32_e32 v10, 0, v4
	v_lshlrev_b32_e32 v4, 6, v16
	s_movk_i32 s1, 0x3c0
	v_and_or_b32 v4, v4, s1, v19
	v_xad_u32 v161, v4, v5, 0
	v_lshl_add_u64 v[4:5], s[24:25], 0, v[130:131]
	v_readlane_b32 s64, v254, 60
	v_lshl_add_u64 v[4:5], v[4:5], 0, v[0:1]
	v_readlane_b32 s76, v253, 8
	v_readlane_b32 s77, v253, 9
	v_readlane_b32 s65, v254, 61
	v_readlane_b32 s66, v254, 62
	v_lshl_add_u64 v[136:137], s[76:77], 0, v[4:5]
	v_lshl_add_u64 v[4:5], s[24:25], 0, v[134:135]
	v_readlane_b32 s67, v254, 63
	v_readlane_b32 s68, v253, 0
	v_readlane_b32 s69, v253, 1
	v_readlane_b32 s70, v253, 2
	v_readlane_b32 s71, v253, 3
	v_readlane_b32 s72, v253, 4
	v_readlane_b32 s73, v253, 5
	v_readlane_b32 s74, v253, 6
	v_readlane_b32 s75, v253, 7
	v_readlane_b32 s78, v253, 10
	v_readlane_b32 s79, v253, 11
	v_lshl_add_u64 v[4:5], v[4:5], 0, v[2:3]
	v_lshl_add_u64 v[138:139], s[76:77], 0, v[4:5]
	v_lshl_add_u64 v[4:5], s[34:35], 0, v[130:131]
	v_readlane_b32 s64, v254, 12
	v_lshl_add_u64 v[0:1], v[4:5], 0, v[0:1]
	v_readlane_b32 s68, v254, 16
	v_readlane_b32 s69, v254, 17
	s_waitcnt vmcnt(6)
	s_lshl_b32 s17, s88, 6
	s_and_b32 s59, s17, 0x3000
	v_lshl_add_u64 v[140:141], s[68:69], 0, v[0:1]
	v_lshl_add_u64 v[0:1], s[34:35], 0, v[134:135]
	v_lshl_add_u64 v[0:1], v[0:1], 0, v[2:3]
	v_lshl_add_u64 v[142:143], s[68:69], 0, v[0:1]
	v_mov_b32_e32 v0, 0
	s_or_b32 s1, s60, 0x800
	s_or_b32 s17, s60, 0x1000
	s_or_b32 s58, s60, 0x1800
	s_mov_b32 s34, -2
	s_mov_b64 s[24:25], 0
	v_add_u32_e32 v163, s59, v6
	v_add_u32_e32 v147, s60, v10
	v_add_u32_e32 v162, s59, v7
	v_add_u32_e32 v152, s59, v8
	v_add_u32_e32 v150, s59, v9
	v_mov_b32_e32 v1, v0
	v_mov_b32_e32 v2, v0
	v_mov_b32_e32 v3, v0
	v_mov_b32_e32 v4, v0
	v_mov_b32_e32 v5, v0
	v_mov_b32_e32 v6, v0
	v_mov_b32_e32 v7, v0
	v_mov_b32_e32 v8, v0
	v_mov_b32_e32 v9, v0
	v_mov_b32_e32 v10, v0
	v_mov_b32_e32 v11, v0
	v_mov_b32_e32 v12, v0
	v_mov_b32_e32 v13, v0
	v_mov_b32_e32 v14, v0
	v_mov_b32_e32 v15, v0
	v_mov_b32_e32 v16, v0
	v_mov_b32_e32 v17, v0
	v_mov_b32_e32 v18, v0
	v_mov_b32_e32 v19, v0
	v_mov_b32_e32 v20, v0
	v_mov_b32_e32 v21, v0
	v_mov_b32_e32 v22, v0
	v_mov_b32_e32 v23, v0
	v_mov_b32_e32 v24, v0
	v_mov_b32_e32 v25, v0
	v_mov_b32_e32 v26, v0
	v_mov_b32_e32 v27, v0
	v_mov_b32_e32 v28, v0
	v_mov_b32_e32 v29, v0
	v_mov_b32_e32 v30, v0
	v_mov_b32_e32 v31, v0
	v_mov_b32_e32 v32, v0
	v_mov_b32_e32 v33, v0
	v_mov_b32_e32 v34, v0
	v_mov_b32_e32 v35, v0
	v_mov_b32_e32 v36, v0
	v_mov_b32_e32 v37, v0
	v_mov_b32_e32 v38, v0
	v_mov_b32_e32 v39, v0
	v_mov_b32_e32 v40, v0
	v_mov_b32_e32 v41, v0
	v_mov_b32_e32 v42, v0
	v_mov_b32_e32 v43, v0
	v_mov_b32_e32 v44, v0
	v_mov_b32_e32 v45, v0
	v_mov_b32_e32 v46, v0
	v_mov_b32_e32 v47, v0
	v_mov_b32_e32 v48, v0
	v_mov_b32_e32 v49, v0
	v_mov_b32_e32 v50, v0
	v_mov_b32_e32 v51, v0
	v_mov_b32_e32 v52, v0
	v_mov_b32_e32 v53, v0
	v_mov_b32_e32 v54, v0
	v_mov_b32_e32 v55, v0
	v_mov_b32_e32 v56, v0
	v_mov_b32_e32 v57, v0
	v_mov_b32_e32 v58, v0
	v_mov_b32_e32 v59, v0
	v_mov_b32_e32 v60, v0
	v_mov_b32_e32 v61, v0
	v_mov_b32_e32 v62, v0
	v_mov_b32_e32 v63, v0
	v_mov_b32_e32 v64, v0
	v_mov_b32_e32 v65, v0
	v_mov_b32_e32 v66, v0
	v_mov_b32_e32 v67, v0
	v_mov_b32_e32 v68, v0
	v_mov_b32_e32 v69, v0
	v_mov_b32_e32 v70, v0
	v_mov_b32_e32 v71, v0
	v_mov_b32_e32 v72, v0
	v_mov_b32_e32 v73, v0
	v_mov_b32_e32 v74, v0
	v_mov_b32_e32 v75, v0
	v_mov_b32_e32 v76, v0
	v_mov_b32_e32 v77, v0
	v_mov_b32_e32 v78, v0
	v_mov_b32_e32 v79, v0
	v_mov_b32_e32 v80, v0
	v_mov_b32_e32 v81, v0
	v_mov_b32_e32 v82, v0
	v_mov_b32_e32 v83, v0
	v_mov_b32_e32 v84, v0
	v_mov_b32_e32 v85, v0
	v_mov_b32_e32 v86, v0
	v_mov_b32_e32 v87, v0
	v_mov_b32_e32 v88, v0
	v_mov_b32_e32 v89, v0
	v_mov_b32_e32 v90, v0
	v_mov_b32_e32 v91, v0
	v_mov_b32_e32 v92, v0
	v_mov_b32_e32 v93, v0
	v_mov_b32_e32 v94, v0
	v_mov_b32_e32 v95, v0
	v_mov_b32_e32 v96, v0
	v_mov_b32_e32 v97, v0
	v_mov_b32_e32 v98, v0
	v_mov_b32_e32 v99, v0
	v_mov_b32_e32 v100, v0
	v_mov_b32_e32 v101, v0
	v_mov_b32_e32 v102, v0
	v_mov_b32_e32 v103, v0
	v_mov_b32_e32 v104, v0
	v_mov_b32_e32 v105, v0
	v_mov_b32_e32 v106, v0
	v_mov_b32_e32 v107, v0
	v_mov_b32_e32 v108, v0
	v_mov_b32_e32 v109, v0
	v_mov_b32_e32 v110, v0
	v_mov_b32_e32 v111, v0
	v_mov_b32_e32 v112, v0
	v_mov_b32_e32 v113, v0
	v_mov_b32_e32 v114, v0
	v_mov_b32_e32 v115, v0
	v_mov_b32_e32 v116, v0
	v_mov_b32_e32 v117, v0
	v_mov_b32_e32 v118, v0
	v_mov_b32_e32 v119, v0
	v_mov_b32_e32 v120, v0
	v_mov_b32_e32 v121, v0
	v_mov_b32_e32 v122, v0
	v_mov_b32_e32 v123, v0
	v_mov_b32_e32 v124, v0
	v_mov_b32_e32 v125, v0
	v_mov_b32_e32 v126, v0
	v_mov_b32_e32 v127, v0
	s_barrier
	v_readlane_b32 s65, v254, 13
	v_readlane_b32 s66, v254, 14
	v_readlane_b32 s67, v254, 15
	v_readlane_b32 s70, v254, 18
	v_readlane_b32 s71, v254, 19
	v_readlane_b32 s72, v254, 20
	v_readlane_b32 s73, v254, 21
	v_readlane_b32 s74, v254, 22
	v_readlane_b32 s75, v254, 23
	v_readlane_b32 s76, v254, 24
	v_readlane_b32 s77, v254, 25
	v_readlane_b32 s78, v254, 26
	v_readlane_b32 s79, v254, 27
	s_nop 0
	s_nop 0
	s_nop 0
	s_nop 0
	s_nop 0
	s_nop 0
	s_nop 0
.LBB0_224:
	ds_read_b128 v[170:173], v163
	ds_read_b128 v[174:177], v163 offset:1024
	ds_read_b128 v[182:185], v163 offset:2048
	ds_read_b128 v[186:189], v163 offset:3072
	v_add_u32_e32 v167, 0xc000, v148
	v_lshl_add_u64 v[178:179], v[140:141], 0, s[24:25]
	v_readfirstlane_b32 s35, v167
	v_add_u32_e32 v164, s1, v161
	v_add_u32_e32 v165, s17, v161
	v_add_u32_e32 v166, s58, v161
	v_lshl_add_u64 v[168:169], v[178:179], 0, s[2:3]
	s_mov_b32 m0, s35
	ds_read_b128 v[190:193], v147
	ds_read_b128 v[194:197], v147 offset:1024
	ds_read_b128 v[198:201], v164
	ds_read_b128 v[202:205], v164 offset:1024
	ds_read_b128 v[206:209], v165
	ds_read_b128 v[210:213], v165 offset:1024
	ds_read_b128 v[214:217], v166
	ds_read_b128 v[218:221], v166 offset:1024
	global_load_lds_dwordx4 v[168:169], off
	v_add_u32_e32 v168, 0xe000, v148
	v_lshl_add_u64 v[238:239], v[142:143], 0, s[24:25]
	v_readfirstlane_b32 s35, v168
	v_lshl_add_u64 v[222:223], v[238:239], 0, s[2:3]
	s_mov_b32 m0, s35
	s_nop 0
	global_load_lds_dwordx4 v[222:223], off
	s_waitcnt lgkmcnt(8)
	s_barrier
	s_waitcnt lgkmcnt(0)
	s_setprio 1
	s_waitcnt lgkmcnt(0)
	v_mfma_f32_16x16x32_bf16 v[124:127], v[170:173], v[190:193], v[124:127]
	v_mfma_f32_16x16x32_bf16 v[120:123], v[182:185], v[190:193], v[120:123]
	v_mfma_f32_16x16x32_bf16 v[116:119], v[170:173], v[198:201], v[116:119]
	v_mfma_f32_16x16x32_bf16 v[112:115], v[182:185], v[198:201], v[112:115]
	v_mfma_f32_16x16x32_bf16 v[108:111], v[170:173], v[206:209], v[108:111]
	v_mfma_f32_16x16x32_bf16 v[104:107], v[182:185], v[206:209], v[104:107]
	v_mfma_f32_16x16x32_bf16 v[100:103], v[170:173], v[214:217], v[100:103]
	v_mfma_f32_16x16x32_bf16 v[96:99], v[182:185], v[214:217], v[96:99]
	v_mfma_f32_16x16x32_bf16 v[124:127], v[174:177], v[194:197], v[124:127]
	v_mfma_f32_16x16x32_bf16 v[120:123], v[186:189], v[194:197], v[120:123]
	v_mfma_f32_16x16x32_bf16 v[116:119], v[174:177], v[202:205], v[116:119]
	v_mfma_f32_16x16x32_bf16 v[112:115], v[186:189], v[202:205], v[112:115]
	v_mfma_f32_16x16x32_bf16 v[108:111], v[174:177], v[210:213], v[108:111]
	v_mfma_f32_16x16x32_bf16 v[104:107], v[186:189], v[210:213], v[104:107]
	v_mfma_f32_16x16x32_bf16 v[100:103], v[174:177], v[218:221], v[100:103]
	v_mfma_f32_16x16x32_bf16 v[96:99], v[186:189], v[218:221], v[96:99]
	s_setprio 0
	s_barrier
	v_lshl_add_u64 v[240:241], v[136:137], 0, s[24:25]
	v_readfirstlane_b32 s35, v146
	v_lshl_add_u64 v[242:243], v[240:241], 0, s[8:9]
	s_mov_b32 m0, s35
	v_add_u32_e32 v169, 0x2000, v146
	ds_read_b128 v[222:225], v162
	ds_read_b128 v[226:229], v162 offset:1024
	ds_read_b128 v[230:233], v162 offset:2048
	ds_read_b128 v[234:237], v162 offset:3072
	global_load_lds_dwordx4 v[242:243], off
	v_lshl_add_u64 v[242:243], v[138:139], 0, s[24:25]
	v_readfirstlane_b32 s35, v169
	v_lshl_add_u64 v[244:245], v[242:243], 0, s[8:9]
	s_mov_b32 m0, s35
	s_nop 0
	global_load_lds_dwordx4 v[244:245], off
	s_barrier
	s_waitcnt lgkmcnt(0)
	s_setprio 1
	s_waitcnt lgkmcnt(0)
	v_mfma_f32_16x16x32_bf16 v[92:95], v[222:225], v[190:193], v[92:95]
	v_mfma_f32_16x16x32_bf16 v[88:91], v[230:233], v[190:193], v[88:91]
	v_mfma_f32_16x16x32_bf16 v[84:87], v[222:225], v[198:201], v[84:87]
	v_mfma_f32_16x16x32_bf16 v[80:83], v[230:233], v[198:201], v[80:83]
	v_mfma_f32_16x16x32_bf16 v[76:79], v[222:225], v[206:209], v[76:79]
	v_mfma_f32_16x16x32_bf16 v[72:75], v[230:233], v[206:209], v[72:75]
	v_mfma_f32_16x16x32_bf16 v[68:71], v[222:225], v[214:217], v[68:71]
	v_mfma_f32_16x16x32_bf16 v[64:67], v[230:233], v[214:217], v[64:67]
	v_mfma_f32_16x16x32_bf16 v[92:95], v[226:229], v[194:197], v[92:95]
	v_mfma_f32_16x16x32_bf16 v[88:91], v[234:237], v[194:197], v[88:91]
	v_mfma_f32_16x16x32_bf16 v[84:87], v[226:229], v[202:205], v[84:87]
	v_mfma_f32_16x16x32_bf16 v[80:83], v[234:237], v[202:205], v[80:83]
	v_mfma_f32_16x16x32_bf16 v[76:79], v[226:229], v[210:213], v[76:79]
	v_mfma_f32_16x16x32_bf16 v[72:75], v[234:237], v[210:213], v[72:75]
	v_mfma_f32_16x16x32_bf16 v[68:71], v[226:229], v[218:221], v[68:71]
	v_mfma_f32_16x16x32_bf16 v[64:67], v[234:237], v[218:221], v[64:67]
	s_setprio 0
	v_readfirstlane_b32 s35, v148
	v_lshl_add_u64 v[244:245], v[178:179], 0, s[8:9]
	s_mov_b32 m0, s35
	v_readfirstlane_b32 s35, v149
	s_barrier
	ds_read_b128 v[190:193], v147 offset:16384
	ds_read_b128 v[194:197], v147 offset:17408
	ds_read_b128 v[198:201], v164 offset:16384
	ds_read_b128 v[202:205], v164 offset:17408
	ds_read_b128 v[206:209], v165 offset:16384
	ds_read_b128 v[210:213], v165 offset:17408
	ds_read_b128 v[214:217], v166 offset:16384
	ds_read_b128 v[218:221], v166 offset:17408
	global_load_lds_dwordx4 v[244:245], off
	v_lshl_add_u64 v[244:245], v[238:239], 0, s[8:9]
	s_mov_b32 m0, s35
	s_nop 0
	global_load_lds_dwordx4 v[244:245], off
	s_barrier
	s_waitcnt lgkmcnt(0)
	s_setprio 1
	s_waitcnt lgkmcnt(0)
	v_mfma_f32_16x16x32_bf16 v[60:63], v[170:173], v[190:193], v[60:63]
	v_mfma_f32_16x16x32_bf16 v[56:59], v[182:185], v[190:193], v[56:59]
	v_mfma_f32_16x16x32_bf16 v[52:55], v[170:173], v[198:201], v[52:55]
	v_mfma_f32_16x16x32_bf16 v[48:51], v[182:185], v[198:201], v[48:51]
	v_mfma_f32_16x16x32_bf16 v[44:47], v[170:173], v[206:209], v[44:47]
	v_mfma_f32_16x16x32_bf16 v[40:43], v[182:185], v[206:209], v[40:43]
	v_mfma_f32_16x16x32_bf16 v[36:39], v[170:173], v[214:217], v[36:39]
	v_mfma_f32_16x16x32_bf16 v[32:35], v[182:185], v[214:217], v[32:35]
	v_mfma_f32_16x16x32_bf16 v[60:63], v[174:177], v[194:197], v[60:63]
	v_mfma_f32_16x16x32_bf16 v[56:59], v[186:189], v[194:197], v[56:59]
	v_mfma_f32_16x16x32_bf16 v[52:55], v[174:177], v[202:205], v[52:55]
	v_mfma_f32_16x16x32_bf16 v[48:51], v[186:189], v[202:205], v[48:51]
	v_mfma_f32_16x16x32_bf16 v[44:47], v[174:177], v[210:213], v[44:47]
	v_mfma_f32_16x16x32_bf16 v[40:43], v[186:189], v[210:213], v[40:43]
	v_mfma_f32_16x16x32_bf16 v[36:39], v[174:177], v[218:221], v[36:39]
	v_mfma_f32_16x16x32_bf16 v[32:35], v[186:189], v[218:221], v[32:35]
	s_setprio 0
	s_barrier
	v_readfirstlane_b32 s35, v151
	v_add_u32_e32 v169, 0x2000, v151
	v_lshl_add_u64 v[170:171], v[240:241], 0, s[10:11]
	s_mov_b32 m0, s35
	v_readfirstlane_b32 s35, v169
	global_load_lds_dwordx4 v[170:171], off
	v_lshl_add_u64 v[170:171], v[242:243], 0, s[10:11]
	s_mov_b32 m0, s35
	s_nop 0
	global_load_lds_dwordx4 v[170:171], off
	s_waitcnt vmcnt(6)
	s_barrier
	s_setprio 1
	v_mfma_f32_16x16x32_bf16 v[28:31], v[222:225], v[190:193], v[28:31]
	v_mfma_f32_16x16x32_bf16 v[24:27], v[230:233], v[190:193], v[24:27]
	v_mfma_f32_16x16x32_bf16 v[20:23], v[222:225], v[198:201], v[20:23]
	v_mfma_f32_16x16x32_bf16 v[16:19], v[230:233], v[198:201], v[16:19]
	v_mfma_f32_16x16x32_bf16 v[12:15], v[222:225], v[206:209], v[12:15]
	v_mfma_f32_16x16x32_bf16 v[8:11], v[230:233], v[206:209], v[8:11]
	v_mfma_f32_16x16x32_bf16 v[4:7], v[222:225], v[214:217], v[4:7]
	v_mfma_f32_16x16x32_bf16 v[0:3], v[230:233], v[214:217], v[0:3]
	v_mfma_f32_16x16x32_bf16 v[28:31], v[226:229], v[194:197], v[28:31]
	v_mfma_f32_16x16x32_bf16 v[24:27], v[234:237], v[194:197], v[24:27]
	v_mfma_f32_16x16x32_bf16 v[20:23], v[226:229], v[202:205], v[20:23]
	v_mfma_f32_16x16x32_bf16 v[16:19], v[234:237], v[202:205], v[16:19]
	v_mfma_f32_16x16x32_bf16 v[12:15], v[226:229], v[210:213], v[12:15]
	v_mfma_f32_16x16x32_bf16 v[8:11], v[234:237], v[210:213], v[8:11]
	v_mfma_f32_16x16x32_bf16 v[4:7], v[226:229], v[218:221], v[4:7]
	v_mfma_f32_16x16x32_bf16 v[0:3], v[234:237], v[218:221], v[0:3]
	s_setprio 0
	s_barrier
	ds_read_b128 v[170:173], v152
	ds_read_b128 v[174:177], v152 offset:1024
	ds_read_b128 v[182:185], v152 offset:2048
	ds_read_b128 v[186:189], v152 offset:3072
	v_readfirstlane_b32 s35, v153
	v_lshl_add_u64 v[222:223], v[178:179], 0, s[10:11]
	s_mov_b32 m0, s35
	v_readfirstlane_b32 s35, v154
	ds_read_b128 v[190:193], v147 offset:32768
	ds_read_b128 v[194:197], v147 offset:33792
	ds_read_b128 v[198:201], v164 offset:32768
	ds_read_b128 v[202:205], v164 offset:33792
	ds_read_b128 v[206:209], v165 offset:32768
	ds_read_b128 v[210:213], v165 offset:33792
	ds_read_b128 v[214:217], v166 offset:32768
	ds_read_b128 v[218:221], v166 offset:33792
	global_load_lds_dwordx4 v[222:223], off
	v_lshl_add_u64 v[222:223], v[238:239], 0, s[10:11]
	s_mov_b32 m0, s35
	s_nop 0
	global_load_lds_dwordx4 v[222:223], off
	s_waitcnt lgkmcnt(8)
	s_barrier
	s_waitcnt lgkmcnt(0)
	s_setprio 1
	s_waitcnt lgkmcnt(0)
	v_mfma_f32_16x16x32_bf16 v[124:127], v[170:173], v[190:193], v[124:127]
	v_mfma_f32_16x16x32_bf16 v[120:123], v[182:185], v[190:193], v[120:123]
	v_mfma_f32_16x16x32_bf16 v[116:119], v[170:173], v[198:201], v[116:119]
	v_mfma_f32_16x16x32_bf16 v[112:115], v[182:185], v[198:201], v[112:115]
	v_mfma_f32_16x16x32_bf16 v[108:111], v[170:173], v[206:209], v[108:111]
	v_mfma_f32_16x16x32_bf16 v[104:107], v[182:185], v[206:209], v[104:107]
	v_mfma_f32_16x16x32_bf16 v[100:103], v[170:173], v[214:217], v[100:103]
	v_mfma_f32_16x16x32_bf16 v[96:99], v[182:185], v[214:217], v[96:99]
	v_mfma_f32_16x16x32_bf16 v[124:127], v[174:177], v[194:197], v[124:127]
	v_mfma_f32_16x16x32_bf16 v[120:123], v[186:189], v[194:197], v[120:123]
	v_mfma_f32_16x16x32_bf16 v[116:119], v[174:177], v[202:205], v[116:119]
	v_mfma_f32_16x16x32_bf16 v[112:115], v[186:189], v[202:205], v[112:115]
	v_mfma_f32_16x16x32_bf16 v[108:111], v[174:177], v[210:213], v[108:111]
	v_mfma_f32_16x16x32_bf16 v[104:107], v[186:189], v[210:213], v[104:107]
	v_mfma_f32_16x16x32_bf16 v[100:103], v[174:177], v[218:221], v[100:103]
	v_mfma_f32_16x16x32_bf16 v[96:99], v[186:189], v[218:221], v[96:99]
	s_setprio 0
	s_barrier
	v_readfirstlane_b32 s35, v155
	v_lshl_add_u64 v[244:245], v[240:241], 0, s[12:13]
	s_mov_b32 m0, s35
	v_readfirstlane_b32 s35, v156
	ds_read_b128 v[222:225], v150
	ds_read_b128 v[226:229], v150 offset:1024
	ds_read_b128 v[230:233], v150 offset:2048
	ds_read_b128 v[234:237], v150 offset:3072
	global_load_lds_dwordx4 v[244:245], off
	v_lshl_add_u64 v[244:245], v[242:243], 0, s[12:13]
	s_mov_b32 m0, s35
	s_nop 0
	global_load_lds_dwordx4 v[244:245], off
	s_barrier
	s_waitcnt lgkmcnt(0)
	s_setprio 1
	s_waitcnt lgkmcnt(0)
	v_mfma_f32_16x16x32_bf16 v[92:95], v[222:225], v[190:193], v[92:95]
	v_mfma_f32_16x16x32_bf16 v[88:91], v[230:233], v[190:193], v[88:91]
	v_mfma_f32_16x16x32_bf16 v[84:87], v[222:225], v[198:201], v[84:87]
	v_mfma_f32_16x16x32_bf16 v[80:83], v[230:233], v[198:201], v[80:83]
	v_mfma_f32_16x16x32_bf16 v[76:79], v[222:225], v[206:209], v[76:79]
	v_mfma_f32_16x16x32_bf16 v[72:75], v[230:233], v[206:209], v[72:75]
	v_mfma_f32_16x16x32_bf16 v[68:71], v[222:225], v[214:217], v[68:71]
	v_mfma_f32_16x16x32_bf16 v[64:67], v[230:233], v[214:217], v[64:67]
	v_mfma_f32_16x16x32_bf16 v[92:95], v[226:229], v[194:197], v[92:95]
	v_mfma_f32_16x16x32_bf16 v[88:91], v[234:237], v[194:197], v[88:91]
	v_mfma_f32_16x16x32_bf16 v[84:87], v[226:229], v[202:205], v[84:87]
	v_mfma_f32_16x16x32_bf16 v[80:83], v[234:237], v[202:205], v[80:83]
	v_mfma_f32_16x16x32_bf16 v[76:79], v[226:229], v[210:213], v[76:79]
	v_mfma_f32_16x16x32_bf16 v[72:75], v[234:237], v[210:213], v[72:75]
	v_mfma_f32_16x16x32_bf16 v[68:71], v[226:229], v[218:221], v[68:71]
	v_mfma_f32_16x16x32_bf16 v[64:67], v[234:237], v[218:221], v[64:67]
	s_setprio 0
	v_readfirstlane_b32 s35, v157
	v_lshl_add_u64 v[178:179], v[178:179], 0, s[12:13]
	s_mov_b32 m0, s35
	v_readfirstlane_b32 s35, v158
	s_barrier
	ds_read_b128 v[190:193], v147 offset:49152
	ds_read_b128 v[194:197], v147 offset:50176
	ds_read_b128 v[198:201], v164 offset:49152
	ds_read_b128 v[202:205], v164 offset:50176
	ds_read_b128 v[206:209], v165 offset:49152
	ds_read_b128 v[210:213], v165 offset:50176
	ds_read_b128 v[214:217], v166 offset:49152
	ds_read_b128 v[218:221], v166 offset:50176
	global_load_lds_dwordx4 v[178:179], off
	v_lshl_add_u64 v[178:179], v[238:239], 0, s[12:13]
	s_mov_b32 m0, s35
	s_nop 0
	global_load_lds_dwordx4 v[178:179], off
	s_barrier
	s_waitcnt lgkmcnt(0)
	s_setprio 1
	s_waitcnt lgkmcnt(0)
	v_mfma_f32_16x16x32_bf16 v[60:63], v[170:173], v[190:193], v[60:63]
	v_mfma_f32_16x16x32_bf16 v[56:59], v[182:185], v[190:193], v[56:59]
	v_mfma_f32_16x16x32_bf16 v[52:55], v[170:173], v[198:201], v[52:55]
	v_mfma_f32_16x16x32_bf16 v[48:51], v[182:185], v[198:201], v[48:51]
	v_mfma_f32_16x16x32_bf16 v[44:47], v[170:173], v[206:209], v[44:47]
	v_mfma_f32_16x16x32_bf16 v[40:43], v[182:185], v[206:209], v[40:43]
	v_mfma_f32_16x16x32_bf16 v[36:39], v[170:173], v[214:217], v[36:39]
	v_mfma_f32_16x16x32_bf16 v[32:35], v[182:185], v[214:217], v[32:35]
	v_mfma_f32_16x16x32_bf16 v[60:63], v[174:177], v[194:197], v[60:63]
	v_mfma_f32_16x16x32_bf16 v[56:59], v[186:189], v[194:197], v[56:59]
	v_mfma_f32_16x16x32_bf16 v[52:55], v[174:177], v[202:205], v[52:55]
	v_mfma_f32_16x16x32_bf16 v[48:51], v[186:189], v[202:205], v[48:51]
	v_mfma_f32_16x16x32_bf16 v[44:47], v[174:177], v[210:213], v[44:47]
	v_mfma_f32_16x16x32_bf16 v[40:43], v[186:189], v[210:213], v[40:43]
	v_mfma_f32_16x16x32_bf16 v[36:39], v[174:177], v[218:221], v[36:39]
	v_mfma_f32_16x16x32_bf16 v[32:35], v[186:189], v[218:221], v[32:35]
	s_setprio 0
	s_barrier
	v_readfirstlane_b32 s35, v159
	v_lshl_add_u64 v[170:171], v[240:241], 0, s[14:15]
	s_mov_b32 m0, s35
	v_readfirstlane_b32 s35, v160
	global_load_lds_dwordx4 v[170:171], off
	v_lshl_add_u64 v[170:171], v[242:243], 0, s[14:15]
	s_mov_b32 m0, s35
	s_nop 0
	global_load_lds_dwordx4 v[170:171], off
	s_waitcnt vmcnt(6)
	s_barrier
	s_setprio 1
	v_mfma_f32_16x16x32_bf16 v[28:31], v[222:225], v[190:193], v[28:31]
	v_mfma_f32_16x16x32_bf16 v[24:27], v[230:233], v[190:193], v[24:27]
	v_mfma_f32_16x16x32_bf16 v[20:23], v[222:225], v[198:201], v[20:23]
	v_mfma_f32_16x16x32_bf16 v[16:19], v[230:233], v[198:201], v[16:19]
	v_mfma_f32_16x16x32_bf16 v[12:15], v[222:225], v[206:209], v[12:15]
	v_mfma_f32_16x16x32_bf16 v[8:11], v[230:233], v[206:209], v[8:11]
	v_mfma_f32_16x16x32_bf16 v[4:7], v[222:225], v[214:217], v[4:7]
	v_mfma_f32_16x16x32_bf16 v[0:3], v[230:233], v[214:217], v[0:3]
	v_mfma_f32_16x16x32_bf16 v[28:31], v[226:229], v[194:197], v[28:31]
	v_mfma_f32_16x16x32_bf16 v[24:27], v[234:237], v[194:197], v[24:27]
	v_mfma_f32_16x16x32_bf16 v[20:23], v[226:229], v[202:205], v[20:23]
	v_mfma_f32_16x16x32_bf16 v[16:19], v[234:237], v[202:205], v[16:19]
	v_mfma_f32_16x16x32_bf16 v[12:15], v[226:229], v[210:213], v[12:15]
	v_mfma_f32_16x16x32_bf16 v[8:11], v[234:237], v[210:213], v[8:11]
	v_mfma_f32_16x16x32_bf16 v[4:7], v[226:229], v[218:221], v[4:7]
	v_mfma_f32_16x16x32_bf16 v[0:3], v[234:237], v[218:221], v[0:3]
	s_setprio 0
	s_add_i32 s34, s34, 2
	s_add_u32 s24, s24, 0x100
	s_addc_u32 s25, s25, 0
	s_cmp_lt_u32 s34, 60
	s_barrier
	s_cbranch_scc1 .LBB0_224
	s_add_u32 s20, s20, 0x1f80
	s_addc_u32 s21, s21, 0
	v_lshl_add_u64 v[130:131], s[20:21], 0, v[130:131]
	v_readfirstlane_b32 s1, v167
	v_lshl_add_u64 v[128:129], v[128:129], 1, v[130:131]
	s_mov_b32 m0, s1
	ds_read_b128 v[136:139], v163
	ds_read_b128 v[140:143], v163 offset:1024
	ds_read_b128 v[154:157], v163 offset:2048
	ds_read_b128 v[158:161], v163 offset:3072
	ds_read_b128 v[170:173], v147
	ds_read_b128 v[174:177], v147 offset:1024
	ds_read_b128 v[182:185], v164
	ds_read_b128 v[186:189], v164 offset:1024
	ds_read_b128 v[190:193], v165
	ds_read_b128 v[194:197], v165 offset:1024
	ds_read_b128 v[198:201], v166
	ds_read_b128 v[202:205], v166 offset:1024
	global_load_lds_dwordx4 v[128:129], off
	v_lshl_add_u64 v[128:129], s[20:21], 0, v[134:135]
	v_readfirstlane_b32 s1, v168
	v_lshl_add_u64 v[128:129], v[132:133], 1, v[128:129]
	s_mov_b32 m0, s1
	s_nop 0
	global_load_lds_dwordx4 v[128:129], off
	s_barrier
	s_waitcnt lgkmcnt(0)
	s_setprio 1
	s_waitcnt lgkmcnt(0)
	v_mfma_f32_16x16x32_bf16 v[124:127], v[136:139], v[170:173], v[124:127]
	v_mfma_f32_16x16x32_bf16 v[120:123], v[154:157], v[170:173], v[120:123]
	v_mfma_f32_16x16x32_bf16 v[116:119], v[136:139], v[182:185], v[116:119]
	v_mfma_f32_16x16x32_bf16 v[112:115], v[154:157], v[182:185], v[112:115]
	v_mfma_f32_16x16x32_bf16 v[100:103], v[136:139], v[198:201], v[100:103]
	v_mfma_f32_16x16x32_bf16 v[96:99], v[154:157], v[198:201], v[96:99]
	v_mfma_f32_16x16x32_bf16 v[124:127], v[140:143], v[174:177], v[124:127]
	v_mfma_f32_16x16x32_bf16 v[120:123], v[158:161], v[174:177], v[120:123]
	v_mfma_f32_16x16x32_bf16 v[116:119], v[140:143], v[186:189], v[116:119]
	v_mfma_f32_16x16x32_bf16 v[112:115], v[158:161], v[186:189], v[112:115]
	v_mfma_f32_16x16x32_bf16 v[108:111], v[136:139], v[190:193], v[108:111]
	v_mfma_f32_16x16x32_bf16 v[104:107], v[154:157], v[190:193], v[104:107]
	v_mfma_f32_16x16x32_bf16 v[100:103], v[140:143], v[202:205], v[100:103]
	v_mfma_f32_16x16x32_bf16 v[96:99], v[158:161], v[202:205], v[96:99]
	v_mfma_f32_16x16x32_bf16 v[128:131], v[140:143], v[194:197], v[108:111]
	v_mfma_f32_16x16x32_bf16 v[132:135], v[158:161], v[194:197], v[104:107]
	s_setprio 0
	s_barrier
	s_nop 1
	ds_read_b128 v[104:107], v162
	ds_read_b128 v[108:111], v162 offset:1024
	ds_read_b128 v[206:209], v162 offset:2048
	ds_read_b128 v[210:213], v162 offset:3072
	s_barrier
	s_waitcnt lgkmcnt(0)
	s_setprio 1
	s_waitcnt lgkmcnt(0)
	v_mfma_f32_16x16x32_bf16 v[84:87], v[104:107], v[182:185], v[84:87]
	v_mfma_f32_16x16x32_bf16 v[80:83], v[206:209], v[182:185], v[80:83]
	v_mfma_f32_16x16x32_bf16 v[68:71], v[104:107], v[198:201], v[68:71]
	v_mfma_f32_16x16x32_bf16 v[64:67], v[206:209], v[198:201], v[64:67]
	v_mfma_f32_16x16x32_bf16 v[92:95], v[104:107], v[170:173], v[92:95]
	v_mfma_f32_16x16x32_bf16 v[88:91], v[206:209], v[170:173], v[88:91]
	v_mfma_f32_16x16x32_bf16 v[84:87], v[108:111], v[186:189], v[84:87]
	v_mfma_f32_16x16x32_bf16 v[80:83], v[210:213], v[186:189], v[80:83]
	v_mfma_f32_16x16x32_bf16 v[76:79], v[104:107], v[190:193], v[76:79]
	v_mfma_f32_16x16x32_bf16 v[72:75], v[206:209], v[190:193], v[72:75]
	v_mfma_f32_16x16x32_bf16 v[68:71], v[108:111], v[202:205], v[68:71]
	v_mfma_f32_16x16x32_bf16 v[64:67], v[210:213], v[202:205], v[64:67]
	v_mfma_f32_16x16x32_bf16 v[214:217], v[108:111], v[174:177], v[92:95]
	v_mfma_f32_16x16x32_bf16 v[168:171], v[210:213], v[174:177], v[88:91]
	v_mfma_f32_16x16x32_bf16 v[172:175], v[108:111], v[194:197], v[76:79]
	v_mfma_f32_16x16x32_bf16 v[176:179], v[210:213], v[194:197], v[72:75]
	s_setprio 0
	s_barrier
	s_nop 0
	ds_read_b128 v[72:75], v147 offset:16384
	ds_read_b128 v[76:79], v147 offset:17408
	ds_read_b128 v[88:91], v164 offset:16384
	ds_read_b128 v[92:95], v164 offset:17408
	ds_read_b128 v[182:185], v165 offset:16384
	ds_read_b128 v[186:189], v165 offset:17408
	ds_read_b128 v[190:193], v166 offset:16384
	ds_read_b128 v[194:197], v166 offset:17408
	s_waitcnt vmcnt(4)
	s_barrier
	s_waitcnt lgkmcnt(0)
	s_setprio 1
	s_waitcnt lgkmcnt(0)
	v_mfma_f32_16x16x32_bf16 v[60:63], v[136:139], v[72:75], v[60:63]
	v_mfma_f32_16x16x32_bf16 v[56:59], v[154:157], v[72:75], v[56:59]
	v_mfma_f32_16x16x32_bf16 v[52:55], v[136:139], v[88:91], v[52:55]
	v_mfma_f32_16x16x32_bf16 v[48:51], v[154:157], v[88:91], v[48:51]
	v_mfma_f32_16x16x32_bf16 v[36:39], v[136:139], v[190:193], v[36:39]
	v_mfma_f32_16x16x32_bf16 v[32:35], v[154:157], v[190:193], v[32:35]
	v_mfma_f32_16x16x32_bf16 v[60:63], v[140:143], v[76:79], v[60:63]
	v_mfma_f32_16x16x32_bf16 v[56:59], v[158:161], v[76:79], v[56:59]
	v_mfma_f32_16x16x32_bf16 v[52:55], v[140:143], v[92:95], v[52:55]
	v_mfma_f32_16x16x32_bf16 v[48:51], v[158:161], v[92:95], v[48:51]
	v_mfma_f32_16x16x32_bf16 v[44:47], v[136:139], v[182:185], v[44:47]
	v_mfma_f32_16x16x32_bf16 v[40:43], v[154:157], v[182:185], v[40:43]
	v_mfma_f32_16x16x32_bf16 v[36:39], v[140:143], v[194:197], v[36:39]
	v_mfma_f32_16x16x32_bf16 v[32:35], v[158:161], v[194:197], v[32:35]
	v_mfma_f32_16x16x32_bf16 v[198:201], v[140:143], v[186:189], v[44:47]
	v_mfma_f32_16x16x32_bf16 v[202:205], v[158:161], v[186:189], v[40:43]
	s_setprio 0
	s_setprio 1
	v_mfma_f32_16x16x32_bf16 v[20:23], v[104:107], v[88:91], v[20:23]
	v_mfma_f32_16x16x32_bf16 v[16:19], v[206:209], v[88:91], v[16:19]
	v_mfma_f32_16x16x32_bf16 v[4:7], v[104:107], v[190:193], v[4:7]
	v_mfma_f32_16x16x32_bf16 v[0:3], v[206:209], v[190:193], v[0:3]
	v_mfma_f32_16x16x32_bf16 v[28:31], v[104:107], v[72:75], v[28:31]
	v_mfma_f32_16x16x32_bf16 v[24:27], v[206:209], v[72:75], v[24:27]
	v_mfma_f32_16x16x32_bf16 v[20:23], v[108:111], v[92:95], v[20:23]
	v_mfma_f32_16x16x32_bf16 v[16:19], v[210:213], v[92:95], v[16:19]
	v_mfma_f32_16x16x32_bf16 v[12:15], v[104:107], v[182:185], v[12:15]
	v_mfma_f32_16x16x32_bf16 v[8:11], v[206:209], v[182:185], v[8:11]
	v_mfma_f32_16x16x32_bf16 v[4:7], v[108:111], v[194:197], v[4:7]
	v_mfma_f32_16x16x32_bf16 v[0:3], v[210:213], v[194:197], v[0:3]
	v_mfma_f32_16x16x32_bf16 v[136:139], v[108:111], v[76:79], v[28:31]
	v_mfma_f32_16x16x32_bf16 v[140:143], v[210:213], v[76:79], v[24:27]
	v_mfma_f32_16x16x32_bf16 v[154:157], v[108:111], v[186:189], v[12:15]
	v_mfma_f32_16x16x32_bf16 v[158:161], v[210:213], v[186:189], v[8:11]
	s_setprio 0
	s_barrier
	s_nop 0
	ds_read_b128 v[8:11], v152
	ds_read_b128 v[12:15], v152 offset:1024
	ds_read_b128 v[182:185], v152 offset:2048
	ds_read_b128 v[186:189], v152 offset:3072
	ds_read_b128 v[24:27], v147 offset:32768
	ds_read_b128 v[28:31], v147 offset:33792
	ds_read_b128 v[40:43], v164 offset:32768
	ds_read_b128 v[44:47], v164 offset:33792
	ds_read_b128 v[190:193], v165 offset:32768
	ds_read_b128 v[194:197], v165 offset:33792
	ds_read_b128 v[206:209], v166 offset:32768
	ds_read_b128 v[210:213], v166 offset:33792
	s_waitcnt vmcnt(2)
	s_barrier
	s_waitcnt lgkmcnt(0)
	s_setprio 1
	s_waitcnt lgkmcnt(0)
	v_mfma_f32_16x16x32_bf16 v[72:75], v[8:11], v[24:27], v[124:127]
	v_mfma_f32_16x16x32_bf16 v[124:127], v[12:15], v[28:31], v[72:75]
	v_mfma_f32_16x16x32_bf16 v[72:75], v[182:185], v[24:27], v[120:123]
	v_mfma_f32_16x16x32_bf16 v[120:123], v[186:189], v[28:31], v[72:75]
	v_mfma_f32_16x16x32_bf16 v[72:75], v[8:11], v[40:43], v[116:119]
	v_mfma_f32_16x16x32_bf16 v[108:111], v[12:15], v[44:47], v[72:75]
	v_mfma_f32_16x16x32_bf16 v[72:75], v[182:185], v[40:43], v[112:115]
	v_mfma_f32_16x16x32_bf16 v[104:107], v[186:189], v[44:47], v[72:75]
	v_mfma_f32_16x16x32_bf16 v[72:75], v[8:11], v[190:193], v[128:131]
	v_mfma_f32_16x16x32_bf16 v[92:95], v[12:15], v[194:197], v[72:75]
	v_mfma_f32_16x16x32_bf16 v[72:75], v[182:185], v[190:193], v[132:135]
	v_mfma_f32_16x16x32_bf16 v[88:91], v[186:189], v[194:197], v[72:75]
	v_mfma_f32_16x16x32_bf16 v[72:75], v[8:11], v[206:209], v[100:103]
	v_mfma_f32_16x16x32_bf16 v[76:79], v[12:15], v[210:213], v[72:75]
	v_mfma_f32_16x16x32_bf16 v[72:75], v[182:185], v[206:209], v[96:99]
	v_mfma_f32_16x16x32_bf16 v[72:75], v[186:189], v[210:213], v[72:75]
	s_setprio 0
	s_barrier
	ds_read_b128 v[128:131], v150
	ds_read_b128 v[132:135], v150 offset:1024
	ds_read_b128 v[218:221], v150 offset:2048
	ds_read_b128 v[148:151], v150 offset:3072
	s_waitcnt vmcnt(0)
	s_barrier
	s_waitcnt lgkmcnt(0)
	s_setprio 1
	s_waitcnt lgkmcnt(0)
	v_mfma_f32_16x16x32_bf16 v[96:99], v[128:131], v[24:27], v[214:217]
	v_mfma_f32_16x16x32_bf16 v[24:27], v[218:221], v[24:27], v[168:171]
	v_mfma_f32_16x16x32_bf16 v[112:115], v[148:151], v[28:31], v[24:27]
	v_mfma_f32_16x16x32_bf16 v[24:27], v[128:131], v[40:43], v[84:87]
	v_mfma_f32_16x16x32_bf16 v[100:103], v[132:135], v[44:47], v[24:27]
	v_mfma_f32_16x16x32_bf16 v[24:27], v[218:221], v[40:43], v[80:83]
	v_mfma_f32_16x16x32_bf16 v[116:119], v[132:135], v[28:31], v[96:99]
	v_mfma_f32_16x16x32_bf16 v[96:99], v[148:151], v[44:47], v[24:27]
	v_mfma_f32_16x16x32_bf16 v[24:27], v[128:131], v[190:193], v[172:175]
	v_mfma_f32_16x16x32_bf16 v[84:87], v[132:135], v[194:197], v[24:27]
	v_mfma_f32_16x16x32_bf16 v[24:27], v[218:221], v[190:193], v[176:179]
	v_mfma_f32_16x16x32_bf16 v[80:83], v[148:151], v[194:197], v[24:27]
	v_mfma_f32_16x16x32_bf16 v[24:27], v[128:131], v[206:209], v[68:71]
	v_mfma_f32_16x16x32_bf16 v[68:71], v[132:135], v[210:213], v[24:27]
	v_mfma_f32_16x16x32_bf16 v[24:27], v[218:221], v[206:209], v[64:67]
	v_mfma_f32_16x16x32_bf16 v[64:67], v[148:151], v[210:213], v[24:27]
	s_setprio 0
	s_barrier
	ds_read_b128 v[168:171], v147 offset:49152
	ds_read_b128 v[172:175], v147 offset:50176
	ds_read_b128 v[176:179], v164 offset:49152
	ds_read_b128 v[190:193], v164 offset:50176
	ds_read_b128 v[194:197], v165 offset:49152
	ds_read_b128 v[162:165], v165 offset:50176
	ds_read_b128 v[206:209], v166 offset:49152
	ds_read_b128 v[210:213], v166 offset:50176
	s_barrier
	s_waitcnt lgkmcnt(0)
	s_setprio 1
	s_waitcnt lgkmcnt(0)
	v_mfma_f32_16x16x32_bf16 v[24:27], v[8:11], v[168:171], v[60:63]
	v_mfma_f32_16x16x32_bf16 v[60:63], v[12:15], v[172:175], v[24:27]
	v_mfma_f32_16x16x32_bf16 v[24:27], v[182:185], v[168:171], v[56:59]
	v_mfma_f32_16x16x32_bf16 v[56:59], v[186:189], v[172:175], v[24:27]
	v_mfma_f32_16x16x32_bf16 v[24:27], v[8:11], v[176:179], v[52:55]
	v_mfma_f32_16x16x32_bf16 v[44:47], v[12:15], v[190:193], v[24:27]
	v_mfma_f32_16x16x32_bf16 v[24:27], v[182:185], v[176:179], v[48:51]
	v_mfma_f32_16x16x32_bf16 v[40:43], v[186:189], v[190:193], v[24:27]
	v_mfma_f32_16x16x32_bf16 v[24:27], v[8:11], v[194:197], v[198:201]
	v_mfma_f32_16x16x32_bf16 v[8:11], v[8:11], v[206:209], v[36:39]
	v_mfma_f32_16x16x32_bf16 v[28:31], v[12:15], v[162:165], v[24:27]
	v_mfma_f32_16x16x32_bf16 v[24:27], v[182:185], v[194:197], v[202:205]
	v_mfma_f32_16x16x32_bf16 v[12:15], v[12:15], v[210:213], v[8:11]
	v_mfma_f32_16x16x32_bf16 v[8:11], v[182:185], v[206:209], v[32:35]
	v_mfma_f32_16x16x32_bf16 v[24:27], v[186:189], v[162:165], v[24:27]
	v_mfma_f32_16x16x32_bf16 v[8:11], v[186:189], v[210:213], v[8:11]
	s_setprio 0
	s_setprio 1
	v_mfma_f32_16x16x32_bf16 v[32:35], v[128:131], v[168:171], v[136:139]
	v_mfma_f32_16x16x32_bf16 v[52:55], v[132:135], v[172:175], v[32:35]
	v_mfma_f32_16x16x32_bf16 v[32:35], v[218:221], v[168:171], v[140:143]
	v_mfma_f32_16x16x32_bf16 v[16:19], v[218:221], v[176:179], v[16:19]
	v_mfma_f32_16x16x32_bf16 v[48:51], v[148:151], v[172:175], v[32:35]
	v_mfma_f32_16x16x32_bf16 v[20:23], v[128:131], v[176:179], v[20:23]
	v_mfma_f32_16x16x32_bf16 v[32:35], v[148:151], v[190:193], v[16:19]
	v_mfma_f32_16x16x32_bf16 v[16:19], v[128:131], v[194:197], v[154:157]
	v_mfma_f32_16x16x32_bf16 v[36:39], v[132:135], v[190:193], v[20:23]
	v_mfma_f32_16x16x32_bf16 v[20:23], v[132:135], v[162:165], v[16:19]
	v_mfma_f32_16x16x32_bf16 v[16:19], v[218:221], v[194:197], v[158:161]
	v_mfma_f32_16x16x32_bf16 v[4:7], v[128:131], v[206:209], v[4:7]
	v_mfma_f32_16x16x32_bf16 v[0:3], v[218:221], v[206:209], v[0:3]
	v_mfma_f32_16x16x32_bf16 v[16:19], v[148:151], v[162:165], v[16:19]
	v_mfma_f32_16x16x32_bf16 v[4:7], v[132:135], v[210:213], v[4:7]
	v_mfma_f32_16x16x32_bf16 v[0:3], v[148:151], v[210:213], v[0:3]
	s_setprio 0
	s_cmpk_gt_u32 s88, 0xff
	s_barrier
	s_cbranch_scc1 .LBB0_220
	s_barrier
	s_branch .LBB0_220
